# stagger WG groups at start of P4 and P5 (8 groups by row-panel index, 1.6us apart) to de-synchronise epilogue store bursts
# speedup vs baseline: 1.0100x; 1.0023x over previous
;     __host__ __device__ bool next(int i, Unit& u) const {
;         if (i >= R) return false;
;         const long L = (long)(rev ? R - 1 - i : i) * G + c; if (L >= nwg) return false;
;         int wgid = (int)L; { const int q = nwg / NXCD, r = nwg % NXCD, xcd = wgid % NXCD, off = wgid / NXCD; wgid = (xcd < r ? xcd * (q + 1) : r * (q + 1) + (xcd - r) * q) + off; }
;         const int nig = WGM * nN, gid = wgid / nig, fm = gid * WGM, gsz = (nM - fm) < WGM ? (nM - fm) : WGM;
;         u.pm = fm + ((wgid % nig) % gsz); u.pn = (wgid % nig) / gsz; u.idx = i; return true;
; __global__ void __launch_bounds__(NWAVES * 64, 2) mega_fwd(Args args) {
;     ...
;           __syncthreads(); }
;         pg8::EpiUp E{F.H, F.stats, tab};
;         pg8::gemm_phase<pg8::EpiUp, pg8::StaticOrder, PG8_ALIGN, PG8_SP2>(F.lds + RING_OFF, g, S, E);
.LBB0_1367:
	s_or_b64 exec, exec, s[6:7]
	s_cmp_gt_i32 s30, 0
	s_cselect_b64 s[0:1], -1, 0
	s_cmpk_lt_i32 s2, 0xc00
	s_cselect_b64 s[4:5], -1, 0
	s_and_b64 s[0:1], s[4:5], s[0:1]
	v_cndmask_b32_e64 v1, 0, 1, s[0:1]
	v_cmp_ne_u32_e64 s[4:5], 1, v1
	s_andn2_b64 vcc, exec, s[0:1]
	v_readfirstlane_b32 s12, v208
	s_waitcnt lgkmcnt(0)
	s_barrier
	s_lshr_b32 s98, s2, 3
	s_and_b32 s98, s98, 7
	s_cbranch_scc0 .Lstg_p4_done
.Lstg_p4_loop:
	s_sleep 50
	s_sub_u32 s98, s98, 1
	s_cmp_lg_u32 s98, 0
	s_cbranch_scc1 .Lstg_p4_loop
.Lstg_p4_done:
	s_cbranch_vccnz .LBB0_1370
	s_lshr_b32 s0, s3, 29
	s_add_i32 s0, s2, s0
	s_ashr_i32 s1, s0, 3
	s_and_b32 s0, s0, -8
	s_sub_i32 s0, s2, s0
	s_cmp_lt_i32 s0, 0
	s_movk_i32 s6, 0x181
	s_cselect_b32 s6, s6, 0x180
	s_mul_i32 s0, s0, s6
	s_add_i32 s0, s0, s1
	s_ashr_i32 s1, s0, 31
	s_lshr_b32 s1, s1, 25
	s_add_i32 s1, s0, s1
	s_ashr_i32 s6, s1, 7
	s_and_b32 s1, s1, 0xff80
	s_sub_i32 s0, s0, s1
	s_bfe_i32 s1, s0, 0x80000
	s_bfe_u32 s1, s1, 0x3000c
	s_add_i32 s1, s0, s1
	s_and_b32 s7, s1, 0xf8
	s_sub_i32 s0, s0, s7
	s_lshl_b32 s6, s6, 3
	s_sext_i32_i8 s0, s0
	s_add_i32 s24, s6, s0
	s_bfe_i32 s0, s1, 0x80000
	s_sext_i32_i16 s0, s0
	s_ashr_i32 s22, s0, 3
	s_and_b64 vcc, exec, s[4:5]
	s_cbranch_vccz .LBB0_1371

; __global__ void __launch_bounds__(NWAVES * 64, 2) mega_fwd(Args args) {
;     ...
;     if (IN(5)) {
;         pg8::Gemm g{F.H, F.Wdn_t, M, D, FF}; pg8::StaticOrder S; S.init(M, D, F.G, (int)blockIdx.x, 1);
.LBB0_1485:
.LBB0_1486:
	s_cmp_lt_i32 s68, 6
	s_cselect_b64 s[0:1], -1, 0
	s_cmp_gt_u32 s33, 5
	s_cselect_b64 s[4:5], -1, 0
	s_and_b64 s[0:1], s[0:1], s[4:5]
	s_andn2_b64 vcc, exec, s[0:1]
	s_cbranch_vccnz .LBB0_1505
	s_abs_i32 s0, s42
	v_cvt_f32_u32_e32 v0, s0
	s_add_i32 s1, s42, 0x2ff
	s_sub_i32 s3, 0xfffffd01, s42
	s_xor_b32 s4, s1, s42
	v_rcp_iflag_f32_e32 v0, v0
	s_max_i32 s1, s1, s3
	s_sub_i32 s3, 0, s0
	s_ashr_i32 s4, s4, 31
	v_mul_f32_e32 v0, 0x4f7ffffe, v0
	v_cvt_u32_f32_e32 v0, v0
	s_nop 0
	v_readfirstlane_b32 s5, v0
	s_mul_i32 s3, s3, s5
	s_mul_hi_u32 s3, s5, s3
	s_add_i32 s5, s5, s3
	s_mul_hi_u32 s3, s1, s5
	s_mul_i32 s5, s3, s0
	s_sub_i32 s1, s1, s5
	s_add_i32 s6, s3, 1
	s_sub_i32 s5, s1, s0
	s_cmp_ge_u32 s1, s0
	s_cselect_b32 s3, s6, s3
	s_cselect_b32 s1, s5, s1
	s_add_i32 s5, s3, 1
	s_cmp_ge_u32 s1, s0
	s_cselect_b32 s0, s5, s3
	s_xor_b32 s0, s0, s4
	s_sub_i32 s3, s0, s4
	s_cmp_lt_i32 s3, 1
	v_readfirstlane_b32 s6, v208
	s_cbranch_scc1 .LBB0_1505
	s_lshr_b32 s98, s2, 3
	s_and_b32 s98, s98, 7
	s_cbranch_scc0 .Lstg_p5_done

; #define PG8_STAGE(bufoff, gbase, voff) do { _Pragma("unroll") for (int _i = 0; _i < 2; ++_i) \
;         __builtin_amdgcn_global_load_lds((const unsigned*)((const char*)(gbase) + (voff)[_i]), (PG8_LAS unsigned*)(lds + (bufoff) + ldsw + _i * 8192), 16, 0, 0); } while (0)
; #define PG8_WAIT_V(n) asm volatile("s_waitcnt vmcnt(" #n ")" ::: "memory")
; #define PG8_BAR __builtin_amdgcn_s_barrier()
;     __host__ __device__ bool next(int i, Unit& u) const {
;         if (i >= R) return false;
;         const long L = (long)(rev ? R - 1 - i : i) * G + c; if (L >= nwg) return false;
;         int wgid = (int)L; { const int q = nwg / NXCD, r = nwg % NXCD, xcd = wgid % NXCD, off = wgid / NXCD; wgid = (xcd < r ? xcd * (q + 1) : r * (q + 1) + (xcd - r) * q) + off; }
;         const int nig = WGM * nN, gid = wgid / nig, fm = gid * WGM, gsz = (nM - fm) < WGM ? (nM - fm) : WGM;
;         u.pm = fm + ((wgid % nig) % gsz); u.pn = (wgid % nig) / gsz; u.idx = i; return true;
; template <class Epi, class Sched, bool ALIGN_EPI = false, bool SP2 = false>
; __device__ __forceinline__ void gemm_phase(PG8_LAS unsigned char* lds, const Gemm g, const Sched& S, const Epi& E) {
;     ...
;     const char* cA = (const char*)g.A + (size_t)cur.pm * tstep; const char* cB = (const char*)g.Bt + (size_t)cur.pn * tstep;
;     S.a_ready(cur);
;     if constexpr (SP2) {
;         PG8_STAGE(PG8_SB(0, 0), cB, voffB); PG8_STAGE(PG8_SB(0, 1), cB + hstep, voffB); PG8_STAGE(PG8_SA(0, 0), cA, voffA); PG8_STAGE(PG8_SA(0, 1), cA + hstep, voffA);
;         if (wr == 1) PG8_BAR;
;         PG8_WAIT_V(2); PG8_BAR;
;         PG8_STAGE(PG8_SB(1, 0), cB + kstep, voffB); PG8_STAGE(PG8_SA(1, 0), cA + kstep, voffA); PG8_STAGE(PG8_SB(1, 1), cB + hstep + kstep, voffB);
.Lstg_p5_done:
	s_add_i32 s0, s3, -1
	s_ashr_i32 s1, s42, 31
	s_mul_i32 s1, s0, s1
	s_mul_hi_u32 s4, s0, s42
	s_add_i32 s4, s4, s1
	s_mul_i32 s0, s0, s42
	s_ashr_i32 s28, s2, 31
	s_add_u32 s0, s0, s2
	s_addc_u32 s1, s4, s28
	v_mov_b64_e32 v[0:1], 0x2ff
	v_cmp_gt_i64_e32 vcc, s[0:1], v[0:1]
	s_cbranch_vccnz .LBB0_1505
	s_ashr_i32 s5, s0, 31
	s_lshr_b32 s5, s5, 29
	s_add_i32 s5, s0, s5
	s_lshr_b32 s4, s6, 6
	s_ashr_i32 s8, s5, 3
	s_and_b32 s5, s5, -8
	s_lshr_b32 s7, s6, 8
	s_lshl_b32 s29, s4, 10
	s_sub_i32 s0, s0, s5
	s_cmp_lt_i32 s0, 0
	s_movk_i32 s30, 0x61
	s_cselect_b32 s5, s30, 0x60
	s_mul_i32 s0, s0, s5
	s_add_i32 s0, s0, s8
	s_ashr_i32 s5, s0, 31
	s_lshr_b32 s5, s5, 27
	s_add_i32 s5, s0, s5
	v_lshrrev_b32_e32 v2, 1, v208
	s_ashr_i32 s8, s5, 5
	s_waitcnt vmcnt(0)
	v_and_b32_e32 v11, 24, v2
	v_lshrrev_b32_e32 v2, 5, v208
	s_lshl_b32 s8, s8, 3
	v_lshlrev_b32_e32 v0, 4, v208
	v_and_b32_e32 v1, 32, v208
	v_and_b32_e32 v2, 4, v2
	s_waitcnt lgkmcnt(0)
	v_bfe_u32 v3, v208, 2, 2
	s_sub_i32 s9, 0xc0, s8
	v_bfe_u32 v10, v208, 2, 4
	v_bitop3_b32 v8, v0, v1, 48 bitop3:0x6c
	v_and_b32_e32 v9, 64, v208
	v_or3_b32 v2, v2, v3, v11
	v_lshrrev_b32_e32 v3, 3, v208
	s_movk_i32 s1, 0x70
	s_min_i32 s9, s9, 8
	v_or_b32_e32 v1, v8, v9
	v_and_or_b32 v4, v3, s1, v10
	s_abs_i32 s10, s9
	s_movk_i32 s1, 0x60
	v_lshl_or_b32 v128, v4, 13, v1
	v_add_u32_e32 v12, 0x2000, v0
	v_cvt_f32_u32_e32 v4, s10
	v_and_or_b32 v3, v3, s1, v2
	v_lshrrev_b32_e32 v0, 7, v12
	s_movk_i32 s1, 0xf0
	v_lshl_or_b32 v130, v3, 13, v1
	v_and_or_b32 v3, v0, s1, v10
	s_movk_i32 s1, 0xe0
	v_and_or_b32 v0, v0, s1, v2
	v_lshl_or_b32 v134, v0, 13, v1
	v_rcp_iflag_f32_e32 v0, v4
	s_sub_i32 s11, 0, s10
	s_andn2_b32 s5, s5, 31
	s_sub_i32 s0, s0, s5
	v_mul_f32_e32 v0, 0x4f7ffffe, v0
	v_cvt_u32_f32_e32 v0, v0
	s_abs_i32 s5, s0
	s_xor_b32 s1, s0, s9
	s_ashr_i32 s1, s1, 31
	v_readfirstlane_b32 s12, v0
	s_mul_i32 s11, s11, s12
	s_mul_hi_u32 s11, s12, s11
	s_add_i32 s12, s12, s11
	s_mul_hi_u32 s11, s5, s12
	s_mul_i32 s12, s11, s10
	s_sub_i32 s5, s5, s12
	s_add_i32 s12, s11, 1
	s_sub_i32 s13, s5, s10
	s_cmp_ge_u32 s5, s10
	s_cselect_b32 s11, s12, s11
	s_cselect_b32 s5, s13, s5
	s_add_i32 s12, s11, 1
	s_cmp_ge_u32 s5, s10
	s_cselect_b32 s5, s12, s11
	s_xor_b32 s5, s5, s1
	s_sub_i32 s18, s5, s1
	s_mul_i32 s1, s18, s9
	s_sub_i32 s0, s0, s1
	s_add_i32 s20, s8, s0
	s_ashr_i32 s21, s20, 31
	s_ashr_i32 s19, s18, 31
	s_lshl_b64 s[0:1], s[20:21], 21
	s_lshl_b64 s[8:9], s[18:19], 21
	s_add_u32 s24, s64, s8
	s_addc_u32 s25, s65, s9
	s_add_i32 s19, s29, 0x100
	s_add_i32 m0, s19, 0x10000
	v_lshl_or_b32 v132, v3, 13, v1
	global_load_lds_dwordx4 v130, s[24:25]
	s_add_i32 m0, s19, 0x12000
	s_add_u32 s8, s24, 0x100000
	global_load_lds_dwordx4 v134, s[24:25]
	s_addc_u32 s9, s25, 0
	s_add_i32 m0, s19, 0x14000
	v_mov_b32_e32 v131, 0
	global_load_lds_dwordx4 v130, s[8:9]
	s_add_i32 m0, s19, 0x16000
	s_add_u32 s22, s50, s0
	s_addc_u32 s23, s51, s1
	s_add_i32 s21, s19, 0x2000
	global_load_lds_dwordx4 v134, s[8:9]
	s_mov_b32 m0, s19
	s_add_u32 s0, s22, 0x100000
	global_load_lds_dwordx4 v128, s[22:23]
	s_mov_b32 m0, s21
	s_addc_u32 s1, s23, 0
	s_add_i32 s31, s19, 0x4000
	global_load_lds_dwordx4 v132, s[22:23]
	s_mov_b32 m0, s31
	s_add_i32 s33, s19, 0x6000
	global_load_lds_dwordx4 v128, s[0:1]
	s_mov_b32 m0, s33
	v_mov_b32_e32 v135, v131
	global_load_lds_dwordx4 v132, s[0:1]
	v_mov_b32_e32 v129, v131
	v_mov_b32_e32 v133, v131
	s_cmp_eq_u32 s7, 1
	s_mov_b32 s9, 0
	s_mov_b32 s8, 0x10000
	v_lshl_add_u64 v[6:7], s[24:25], 0, v[130:131]
	v_lshl_add_u64 v[2:3], s[24:25], 0, v[134:135]
	s_mov_b32 s10, 0x14000
	v_lshl_add_u64 v[0:1], s[22:23], 0, v[128:129]
	s_cselect_b64 s[0:1], -1, 0
	s_cmp_lg_u32 s7, 1
	v_lshl_add_u64 v[4:5], s[22:23], 0, v[132:133]
	s_cbranch_scc1 .LBB0_1491
	s_barrier
